# attention: one 16-lane returning atomic_add 0 probes all queue counters at k=1; exhausted queues skipped without a claiming atomic
# speedup vs baseline: 1.0437x; 1.0437x over previous
; __device__ __forceinline__ void phase_attn(const Ctx& C, const float* relb  , int layer) {
;     ...
;       for (int k = 0; k < 8; ++k) { const int x = (((int)blockIdx.x & 7) + k * (1 + 2 * (((int)blockIdx.x >> 3) & 3))) & 7;
;           unsigned* qb_ = (unsigned*)(ws_ + WS_BAR) + WQ_WORD + 64 * (8 * layer + x);
;           unsigned* qa_ = (unsigned*)(ws_ + WS_BAR) + WQ_WORD + 64 * (16 + 8 * layer + x);
;           for (;;) {
;               unsigned idx = 0;
;               if (lane == 0) idx = __hip_atomic_fetch_add(qb_, 1u, __ATOMIC_RELAXED, __HIP_MEMORY_SCOPE_AGENT);
;               idx = (unsigned)__builtin_amdgcn_readfirstlane((int)idx);
;               if (idx >= (unsigned)per_q) break;
.LBB0_262:
	s_cmp_lg_u32 s19, 1
	s_cbranch_scc1 .Lq_noprobe
	v_readlane_b32 s98, v255, 43
	v_readlane_b32 s99, v255, 44
	v_readlane_b32 s100, v255, 47
	v_and_b32_e32 v226, 7, v162
	v_lshlrev_b32_e32 v226, 8, v226
	v_bfe_u32 v227, v162, 3, 1
	v_lshl_or_b32 v226, v227, 12, v226
	v_mov_b32_e32 v228, 0
	v_mov_b32_e32 v224, 0
	s_lshl_b32 s100, s100, 2
	s_add_u32 s98, s98, s100
	s_addc_u32 s99, s99, 0
	s_mov_b64 s[100:101], exec
	s_mov_b64 exec, 0xffff
	s_nop 4
	global_atomic_add v224, v226, v228, s[98:99] sc0
	s_mov_b64 exec, s[100:101]
	s_waitcnt vmcnt(0)
.Lq_noprobe:
	v_readlane_b32 s2, v255, 7
	s_mul_i32 s2, s19, s2
	v_readlane_b32 s3, v254, 0
	s_add_i32 s2, s2, s3
	s_mov_b32 s1, s78
	s_and_b32 s78, s2, 7
	s_lshl_b32 s2, s78, 6
	v_readlane_b32 s3, v255, 47
	s_or_b32 s10, s2, s3
	s_lshl_b64 s[2:3], s[10:11], 2
	v_readlane_b32 s10, v255, 43
	s_add_u32 s20, s10, s2
	v_readlane_b32 s2, v255, 44
	s_addc_u32 s21, s2, s3
	s_lshl_b32 s2, s78, 12
	s_mul_i32 s3, s78, 0x1800000
	s_add_u32 s12, s14, s3
	s_addc_u32 s13, s15, 0
	v_lshl_add_u64 v[134:135], v[116:117], 1, s[12:13]
	s_mov_b64 s[12:13], 0x1400
	s_lshl_b32 s10, s78, 14
	v_lshl_add_u64 v[98:99], v[134:135], 0, s[12:13]
	v_or_b32_e32 v136, s2, v114
	v_lshl_add_u64 v[100:101], v[130:131], 0, s[10:11]
	s_mov_b32 s98, 0
	s_mov_b32 s99, 0
	s_cmp_eq_u32 s19, 0
	s_cbranch_scc1 .Lq_go
	s_add_i32 s100, s78, 8
	v_readlane_b32 s98, v224, s78
	v_readlane_b32 s99, v224, s100
	s_nop 0
.Lq_go:
	s_cmpk_gt_u32 s98, 0x3ff
	s_cbranch_scc1 .LBB0_299
	s_branch .LBB0_265
